# stack: interleaved softmax chains + LDS bias table + RMSNorm next-row prefetch on top of previous best
# baseline (speedup 1.0000x reference)
.LBB0_84:
	v_readfirstlane_b32 s4, v34
	v_readlane_b32 s98, v250, 21
	v_readlane_b32 s99, v250, 22
	v_lshrrev_b32_e32 v81, 1, v50
	s_nop 3
	s_lshl_b32 s5, s4, 13
	s_add_u32 s8, s98, s5
	s_addc_u32 s9, s99, 0
	s_sub_i32 s5, s4, 0x4000
	s_lshl_b32 s5, s5, 13
	s_add_u32 s35, s48, s5
	s_addc_u32 s41, s49, 0
	s_cmp_lt_u32 s4, 0x4000
	s_cselect_b32 s8, s8, s35
	s_cselect_b32 s9, s9, s41
	global_load_dwordx4 v[206:209], v50, s[8:9]
	global_load_dwordx4 v[210:213], v50, s[8:9] offset:1024
	global_load_dwordx4 v[214:217], v50, s[8:9] offset:2048
	global_load_dwordx4 v[218:221], v50, s[8:9] offset:3072
	global_load_dwordx4 v[222:225], v58, s[8:9]
	global_load_dwordx4 v[226:229], v58, s[8:9] offset:1024
	global_load_dwordx4 v[242:245], v58, s[8:9] offset:2048
	global_load_dwordx4 v[246:249], v58, s[8:9] offset:3072
	s_waitcnt vmcnt(0)
.Lnorm_loop:
	s_min_u32 s5, s4, 0x4000
	s_lshr_b32 s5, s5, 11
	s_mul_i32 s5, s5, 0x6000
	s_add_u32 s10, s6, s5
	s_addc_u32 s11, s7, 0
	s_add_u32 s86, s10, 0x2000
	s_addc_u32 s87, s11, 0
	s_lshl_b32 s5, s4, 12
	s_add_u32 s100, s96, s5
	s_addc_u32 s101, s97, 0
	global_load_dwordx4 v[94:97], v[36:37], off
	global_load_dwordx4 v[126:129], v50, s[10:11]
	global_load_dwordx4 v[158:161], v50, s[86:87]
	global_load_dwordx4 v[98:101], v[36:37], off offset:1024
	global_load_dwordx4 v[130:133], v50, s[10:11] offset:1024
	global_load_dwordx4 v[162:165], v50, s[86:87] offset:1024
	global_load_dwordx4 v[102:105], v[36:37], off offset:2048
	global_load_dwordx4 v[134:137], v50, s[10:11] offset:2048
	global_load_dwordx4 v[166:169], v50, s[86:87] offset:2048
	global_load_dwordx4 v[106:109], v[36:37], off offset:3072
	global_load_dwordx4 v[138:141], v50, s[10:11] offset:3072
	global_load_dwordx4 v[170:173], v50, s[86:87] offset:3072
	global_load_dwordx4 v[110:113], v[38:39], off
	global_load_dwordx4 v[142:145], v58, s[10:11]
	global_load_dwordx4 v[174:177], v58, s[86:87]
	global_load_dwordx4 v[114:117], v[38:39], off offset:1024
	global_load_dwordx4 v[146:149], v58, s[10:11] offset:1024
	global_load_dwordx4 v[178:181], v58, s[86:87] offset:1024
	global_load_dwordx4 v[118:121], v[38:39], off offset:2048
	global_load_dwordx4 v[150:153], v58, s[10:11] offset:2048
	global_load_dwordx4 v[182:185], v58, s[86:87] offset:2048
	global_load_dwordx4 v[122:125], v[38:39], off offset:3072
	global_load_dwordx4 v[154:157], v58, s[10:11] offset:3072
	global_load_dwordx4 v[186:189], v58, s[86:87] offset:3072
	s_waitcnt vmcnt(32)
	v_mov_b32_e32 v30, v206
	v_mov_b32_e32 v31, v207
	v_mov_b32_e32 v32, v208
	v_mov_b32_e32 v33, v209
	v_mov_b32_e32 v26, v210
	v_mov_b32_e32 v27, v211
	v_mov_b32_e32 v28, v212
	v_mov_b32_e32 v29, v213
	v_mov_b32_e32 v22, v214
	v_mov_b32_e32 v23, v215
	v_mov_b32_e32 v24, v216
	v_mov_b32_e32 v25, v217
	v_mov_b32_e32 v18, v218
	v_mov_b32_e32 v19, v219
	v_mov_b32_e32 v20, v220
	v_mov_b32_e32 v21, v221
	v_mov_b32_e32 v14, v222
	v_mov_b32_e32 v15, v223
	v_mov_b32_e32 v16, v224
	v_mov_b32_e32 v17, v225
	v_mov_b32_e32 v6, v226
	v_mov_b32_e32 v7, v227
	v_mov_b32_e32 v8, v228
	v_mov_b32_e32 v9, v229
	v_mov_b32_e32 v82, v242
	v_mov_b32_e32 v83, v243
	v_mov_b32_e32 v84, v244
	v_mov_b32_e32 v85, v245
	v_mov_b32_e32 v86, v246
	v_mov_b32_e32 v87, v247
	v_mov_b32_e32 v88, v248
	v_mov_b32_e32 v89, v249
	s_add_i32 s32, s4, s88
	s_cmp_gt_u32 s32, s12
	s_cselect_b32 s5, s4, s32
	s_lshl_b32 s35, s5, 13
	s_add_u32 s8, s98, s35
	s_addc_u32 s9, s99, 0
	s_sub_i32 s35, s5, 0x4000
	s_lshl_b32 s35, s35, 13
	s_add_u32 s35, s48, s35
	s_addc_u32 s41, s49, 0
	s_cmp_lt_u32 s5, 0x4000
	s_cselect_b32 s8, s8, s35
	s_cselect_b32 s9, s9, s41
	global_load_dwordx4 v[206:209], v50, s[8:9]
	global_load_dwordx4 v[210:213], v50, s[8:9] offset:1024
	global_load_dwordx4 v[214:217], v50, s[8:9] offset:2048
	global_load_dwordx4 v[218:221], v50, s[8:9] offset:3072
	global_load_dwordx4 v[222:225], v58, s[8:9]
	global_load_dwordx4 v[226:229], v58, s[8:9] offset:1024
	global_load_dwordx4 v[242:245], v58, s[8:9] offset:2048
	global_load_dwordx4 v[246:249], v58, s[8:9] offset:3072
	v_mul_f32_e32 v4, v31, v31
	v_mul_f32_e32 v5, v27, v27
	v_fmac_f32_e32 v4, v30, v30
	v_fmac_f32_e32 v5, v26, v26
	v_fmac_f32_e32 v4, v32, v32
	v_fmac_f32_e32 v5, v28, v28
	v_fmac_f32_e32 v4, v33, v33
	v_fmac_f32_e32 v5, v29, v29
	v_add_f32_e32 v4, v4, v5
	v_mul_f32_e32 v5, v23, v23
	v_fmac_f32_e32 v5, v22, v22
	v_fmac_f32_e32 v5, v24, v24
	v_fmac_f32_e32 v5, v25, v25
	v_add_f32_e32 v4, v4, v5
	v_mul_f32_e32 v5, v19, v19
	v_fmac_f32_e32 v5, v18, v18
	v_fmac_f32_e32 v5, v20, v20
	v_fmac_f32_e32 v5, v21, v21
	v_mov_b32_e32 v10, v15
	v_mov_b32_e32 v11, v7
	v_add_f32_e32 v12, v4, v5
	v_mov_b32_e32 v4, v14
	v_mov_b32_e32 v5, v6
	v_pk_mul_f32 v[10:11], v[10:11], v[10:11]
	s_nop 0
	v_pk_fma_f32 v[4:5], v[4:5], v[4:5], v[10:11]
	v_mov_b32_e32 v10, v16
	v_mov_b32_e32 v11, v8
	v_pk_fma_f32 v[4:5], v[10:11], v[10:11], v[4:5]
	v_mov_b32_e32 v10, v17
	v_mov_b32_e32 v11, v9
	v_pk_fma_f32 v[4:5], v[10:11], v[10:11], v[4:5]
	s_nop 0
	v_add_f32_e32 v4, v12, v4
	v_add_f32_e32 v66, v4, v5
	v_mov_b32_e32 v74, v83
	v_mov_b32_e32 v75, v87
	v_mov_b32_e32 v70, v82
	v_mov_b32_e32 v71, v86
	v_pk_mul_f32 v[74:75], v[74:75], v[74:75]
	s_nop 0
	v_pk_fma_f32 v[70:71], v[70:71], v[70:71], v[74:75]
	v_mov_b32_e32 v74, v84
	v_mov_b32_e32 v75, v88
	v_pk_fma_f32 v[70:71], v[74:75], v[74:75], v[70:71]
	v_mov_b32_e32 v74, v85
	v_mov_b32_e32 v75, v89
	v_pk_fma_f32 v[70:71], v[74:75], v[74:75], v[70:71]
	s_nop 0
	v_add_f32_e32 v66, v66, v70
	v_add_f32_e32 v66, v66, v71
	ds_bpermute_b32 v70, v67, v66
	s_waitcnt lgkmcnt(0)
	v_add_f32_e32 v66, v66, v70
	ds_bpermute_b32 v70, v76, v66
	s_waitcnt lgkmcnt(0)
	v_add_f32_e32 v66, v66, v70
	ds_bpermute_b32 v70, v77, v66
	s_waitcnt lgkmcnt(0)
	v_add_f32_e32 v66, v66, v70
	ds_bpermute_b32 v70, v78, v66
	s_waitcnt lgkmcnt(0)
	v_add_f32_e32 v66, v66, v70
	ds_bpermute_b32 v70, v79, v66
	s_waitcnt lgkmcnt(0)
	v_add_f32_e32 v66, v66, v70
	ds_bpermute_b32 v70, v80, v66
	s_waitcnt lgkmcnt(0)
	v_add_f32_e32 v66, v66, v70
	v_fmamk_f32 v66, v66, 0x3a000000, v230
	v_cmp_gt_f32_e32 vcc, s70, v66
	v_mul_f32_e32 v70, 0x4b800000, v66
	s_nop 0
	v_cndmask_b32_e32 v66, v66, v70, vcc
	v_rsq_f32_e32 v66, v66
	s_nop 0
	v_mul_f32_e32 v70, 0x45800000, v66
	v_cndmask_b32_e32 v66, v66, v70, vcc
	v_pk_mul_f32 v[30:31], v[30:31], v[66:67] op_sel_hi:[1,0]
	v_pk_mul_f32 v[32:33], v[32:33], v[66:67] op_sel_hi:[1,0]
	v_pk_mul_f32 v[26:27], v[26:27], v[66:67] op_sel_hi:[1,0]
	v_pk_mul_f32 v[28:29], v[28:29], v[66:67] op_sel_hi:[1,0]
	v_pk_mul_f32 v[22:23], v[22:23], v[66:67] op_sel_hi:[1,0]
	v_pk_mul_f32 v[24:25], v[24:25], v[66:67] op_sel_hi:[1,0]
	v_pk_mul_f32 v[18:19], v[18:19], v[66:67] op_sel_hi:[1,0]
	v_pk_mul_f32 v[20:21], v[20:21], v[66:67] op_sel_hi:[1,0]
	v_pk_mul_f32 v[14:15], v[14:15], v[66:67] op_sel_hi:[1,0]
	v_pk_mul_f32 v[16:17], v[16:17], v[66:67] op_sel_hi:[1,0]
	v_pk_mul_f32 v[6:7], v[6:7], v[66:67] op_sel_hi:[1,0]
	v_pk_mul_f32 v[8:9], v[8:9], v[66:67] op_sel_hi:[1,0]
	v_pk_mul_f32 v[82:83], v[82:83], v[66:67] op_sel_hi:[1,0]
	v_pk_mul_f32 v[84:85], v[84:85], v[66:67] op_sel_hi:[1,0]
	v_pk_mul_f32 v[86:87], v[86:87], v[66:67] op_sel_hi:[1,0]
	v_pk_mul_f32 v[88:89], v[88:89], v[66:67] op_sel_hi:[1,0]
	s_waitcnt vmcnt(29)
	v_pk_mul_f32 v[30:31], v[94:95], v[30:31]
	v_pk_mul_f32 v[32:33], v[96:97], v[32:33]
	v_pk_add_f32 v[4:5], v[158:159], 1.0 op_sel_hi:[1,0]
	v_pk_add_f32 v[10:11], v[160:161], 1.0 op_sel_hi:[1,0]
	v_pk_fma_f32 v[30:31], v[4:5], v[30:31], v[126:127]
	v_pk_fma_f32 v[32:33], v[10:11], v[32:33], v[128:129]
	v_cvt_pk_bf16_f32 v12, v30, v31
	v_cvt_pk_bf16_f32 v13, v32, v33
	global_store_dwordx2 v81, v[12:13], s[100:101]
	s_waitcnt vmcnt(27)
	v_pk_mul_f32 v[26:27], v[98:99], v[26:27]
	v_pk_mul_f32 v[28:29], v[100:101], v[28:29]
	v_pk_add_f32 v[4:5], v[162:163], 1.0 op_sel_hi:[1,0]
	v_pk_add_f32 v[10:11], v[164:165], 1.0 op_sel_hi:[1,0]
	v_pk_fma_f32 v[26:27], v[4:5], v[26:27], v[130:131]
	v_pk_fma_f32 v[28:29], v[10:11], v[28:29], v[132:133]
	v_cvt_pk_bf16_f32 v12, v26, v27
	v_cvt_pk_bf16_f32 v13, v28, v29
	global_store_dwordx2 v81, v[12:13], s[100:101] offset:512
	s_waitcnt vmcnt(25)
	v_pk_mul_f32 v[22:23], v[102:103], v[22:23]
	v_pk_mul_f32 v[24:25], v[104:105], v[24:25]
	v_pk_add_f32 v[4:5], v[166:167], 1.0 op_sel_hi:[1,0]
	v_pk_add_f32 v[10:11], v[168:169], 1.0 op_sel_hi:[1,0]
	v_pk_fma_f32 v[22:23], v[4:5], v[22:23], v[134:135]
	v_pk_fma_f32 v[24:25], v[10:11], v[24:25], v[136:137]
	v_cvt_pk_bf16_f32 v12, v22, v23
	v_cvt_pk_bf16_f32 v13, v24, v25
	global_store_dwordx2 v81, v[12:13], s[100:101] offset:1024
	s_waitcnt vmcnt(23)
	v_pk_mul_f32 v[18:19], v[106:107], v[18:19]
	v_pk_mul_f32 v[20:21], v[108:109], v[20:21]
	v_pk_add_f32 v[4:5], v[170:171], 1.0 op_sel_hi:[1,0]
	v_pk_add_f32 v[10:11], v[172:173], 1.0 op_sel_hi:[1,0]
	v_pk_fma_f32 v[18:19], v[4:5], v[18:19], v[138:139]
	v_pk_fma_f32 v[20:21], v[10:11], v[20:21], v[140:141]
	v_cvt_pk_bf16_f32 v12, v18, v19
	v_cvt_pk_bf16_f32 v13, v20, v21
	global_store_dwordx2 v81, v[12:13], s[100:101] offset:1536
	s_waitcnt vmcnt(21)
	v_pk_mul_f32 v[14:15], v[110:111], v[14:15]
	v_pk_mul_f32 v[16:17], v[112:113], v[16:17]
	v_pk_add_f32 v[4:5], v[174:175], 1.0 op_sel_hi:[1,0]
	v_pk_add_f32 v[10:11], v[176:177], 1.0 op_sel_hi:[1,0]
	v_pk_fma_f32 v[14:15], v[4:5], v[14:15], v[142:143]
	v_pk_fma_f32 v[16:17], v[10:11], v[16:17], v[144:145]
	v_cvt_pk_bf16_f32 v12, v14, v15
	v_cvt_pk_bf16_f32 v13, v16, v17
	global_store_dwordx2 v81, v[12:13], s[100:101] offset:2048
	s_waitcnt vmcnt(19)
	v_pk_mul_f32 v[6:7], v[114:115], v[6:7]
	v_pk_mul_f32 v[8:9], v[116:117], v[8:9]
	v_pk_add_f32 v[4:5], v[178:179], 1.0 op_sel_hi:[1,0]
	v_pk_add_f32 v[10:11], v[180:181], 1.0 op_sel_hi:[1,0]
	v_pk_fma_f32 v[6:7], v[4:5], v[6:7], v[146:147]
	v_pk_fma_f32 v[8:9], v[10:11], v[8:9], v[148:149]
	v_cvt_pk_bf16_f32 v12, v6, v7
	v_cvt_pk_bf16_f32 v13, v8, v9
	global_store_dwordx2 v81, v[12:13], s[100:101] offset:2560
	s_waitcnt vmcnt(17)
	v_pk_mul_f32 v[82:83], v[118:119], v[82:83]
	v_pk_mul_f32 v[84:85], v[120:121], v[84:85]
	v_pk_add_f32 v[4:5], v[182:183], 1.0 op_sel_hi:[1,0]
	v_pk_add_f32 v[10:11], v[184:185], 1.0 op_sel_hi:[1,0]
	v_pk_fma_f32 v[82:83], v[4:5], v[82:83], v[150:151]
	v_pk_fma_f32 v[84:85], v[10:11], v[84:85], v[152:153]
	v_cvt_pk_bf16_f32 v12, v82, v83
	v_cvt_pk_bf16_f32 v13, v84, v85
	global_store_dwordx2 v81, v[12:13], s[100:101] offset:3072
	s_waitcnt vmcnt(15)
	v_pk_mul_f32 v[86:87], v[122:123], v[86:87]
	v_pk_mul_f32 v[88:89], v[124:125], v[88:89]
	v_pk_add_f32 v[4:5], v[186:187], 1.0 op_sel_hi:[1,0]
	v_pk_add_f32 v[10:11], v[188:189], 1.0 op_sel_hi:[1,0]
	v_pk_fma_f32 v[86:87], v[4:5], v[86:87], v[154:155]
	v_pk_fma_f32 v[88:89], v[10:11], v[88:89], v[156:157]
	v_cvt_pk_bf16_f32 v12, v86, v87
	v_cvt_pk_bf16_f32 v13, v88, v89
	global_store_dwordx2 v81, v[12:13], s[100:101] offset:3584
	s_mov_b32 s4, s32
	s_cmp_le_u32 s4, s12
	s_cbranch_scc1 .Lnorm_loop
	s_branch .LBB0_86

.LBB0_281:
	s_and_b32 s23, s34, 0xfffffe07
	s_and_b32 s27, s34, 0x38
	s_lshl_b32 s27, s27, 3
	s_or_b32 s23, s23, s27
	s_and_b32 s27, s34, 0x1c0
	s_lshr_b32 s27, s27, 3
	s_or_b32 s23, s23, s27
	s_lshr_b32 s0, s23, 1
	s_and_b32 s6, s0, 30
	s_ashr_i32 s4, s23, 9
	s_lshl_b32 s5, s4, 11
	s_lshl_b32 s1, s6, 6
	s_or_b32 s7, s1, s5
	s_lshl_b32 s1, s23, 4
	s_and_b32 s1, s1, 48
	s_or_b32 s7, s7, s1
	s_bfe_u32 s0, s23, 0x30006
	v_or_b32_e32 v184, s7, v192
	v_mov_b64_e32 v[30:31], s[50:51]
	v_mad_i64_i32 v[186:187], s[8:9], v184, s37, v[30:31]
	s_lshl_b32 s42, s0, 8
	v_or_b32_e32 v180, 64, v184
	v_mad_i64_i32 v[182:183], s[8:9], v180, s37, v[30:31]
	v_sub_u32_e64 v111, s6, 3 clamp
	v_sub_u32_e64 v112, s6, 4 clamp
	v_lshlrev_b32_e32 v194, 1, v170
	v_readfirstlane_b32 s6, v111
	v_readfirstlane_b32 s7, v112
	s_min_u32 s14, s6, 24
	s_min_u32 s15, s7, 24
	s_sub_i32 s59, s14, s15
	s_lshl_b32 s13, s0, 7
	s_add_i32 s2, s59, 8
	v_lshl_add_u64 v[2:3], v[186:187], 0, s[42:43]
	v_lshl_add_u64 v[4:5], v[182:183], 0, s[42:43]
	v_lshl_add_u64 v[2:3], v[2:3], 0, v[194:195]
	v_lshl_add_u64 v[4:5], v[4:5], 0, v[194:195]
	v_lshl_add_u64 v[2:3], v[2:3], 0, s[10:11]
	v_lshl_add_u64 v[4:5], v[4:5], 0, s[10:11]
	s_barrier
	s_bfe_u32 s27, s23, 0x30003
	s_lshl_b32 s27, s27, 2
	s_sub_i32 s42, s27, 4
	s_max_i32 s42, s42, 0
	s_min_i32 s32, s42, 24
	s_sub_i32 s42, s27, 1
	s_max_i32 s42, s42, 0
	s_min_i32 s42, s42, 24
	s_add_i32 s42, s42, 8
	s_sub_i32 s78, s42, s32
	s_mov_b32 s71, 0
	s_mov_b32 s98, 0x1000
	s_mov_b32 s99, 0x1000
	v_or_b32_e32 v242, v172, v192
	s_lshl_b32 s27, s12, 6
	v_add_u32_e32 v242, s27, v242
	v_min_u32_e32 v243, 0x1d0, v242
	v_lshlrev_b32_e32 v243, 2, v243
	v_readlane_b32 s10, v252, 24
	v_readlane_b32 s11, v252, 25
	s_bfe_u32 s42, s23, 0x30006
	s_or_b32 s27, s17, s42
	s_mul_i32 s27, s27, 0x744
	s_add_u32 s10, s10, s27
	s_addc_u32 s11, s11, 0
	global_load_dword v248, v243, s[10:11]
	s_bfe_u32 s27, s12, 0x10001
	s_lshl_b32 s27, s27, 3
	v_lshrrev_b32_e32 v242, 1, v197
	v_sub_u32_e32 v243, v192, v242
	v_and_b32_e32 v243, 3, v243
	v_add_u32_e32 v244, v243, v242
	v_add_u32_e32 v244, s27, v244
	v_and_b32_e32 v244, 15, v244
	v_xor_b32_e32 v245, v192, v244
	v_and_b32_e32 v245, 12, v245
	v_or_b32_e32 v243, v243, v245
	v_lshlrev_b32_e32 v243, 4, v243
	v_lshrrev_b32_e32 v246, 2, v197
	s_lshl_b32 s27, s12, 2
	v_add_u32_e32 v246, s27, v246
	v_mul_u32_u24_e32 v246, 0x6800, v246
	v_add_u32_e32 v229, v246, v243
	v_or_b32_e32 v242, v172, v192
	v_lshrrev_b32_e32 v243, 3, v242
	v_and_b32_e32 v244, 6, v243
	v_and_b32_e32 v245, 7, v242
	v_sub_u32_e32 v245, v245, v244
	v_and_b32_e32 v245, 7, v245
	v_lshlrev_b32_e32 v245, 4, v245
	s_lshl_b32 s27, s12, 3
	v_add_u32_e32 v243, s27, v243
	v_mul_u32_u24_e32 v243, 0x9000, v243
	v_add_u32_e32 v254, v243, v245
	s_mov_b32 s9, 0
	s_sub_i32 s27, s9, s78
	s_lshr_b32 s42, s23, 9
	s_lshl_b32 s101, s42, 2
	s_add_i32 s27, s27, s101
	s_add_i32 s27, s27, 0x100
	s_lshl_b32 s42, s42, 5
	s_add_i32 s42, s42, s32
	s_add_i32 s42, s42, s9
	s_cmp_lt_u32 s9, s78
	s_cselect_b32 s27, s42, s27
	s_lshl_b32 s27, s27, 6
	s_mul_i32 s42, s27, s37
	s_add_u32 s10, s50, s42
	s_addc_u32 s11, s51, 0
	s_lshl_b32 s101, s13, 1
	s_add_i32 s101, s101, 0x2800
	s_add_u32 s10, s10, s101
	s_addc_u32 s11, s11, 0
	s_lshl_b32 s8, s12, 10
	s_add_i32 s8, s8, s98
	s_mov_b32 m0, s8
	s_add_i32 s8, s8, 0x2000
	global_load_lds_dwordx4 v229, s[10:11]
	s_mov_b32 m0, s8
	s_add_u32 s10, s10, 0xd0000
	s_addc_u32 s11, s11, 0
	global_load_lds_dwordx4 v229, s[10:11]
	v_readlane_b32 s10, v252, 55
	v_readlane_b32 s11, v252, 56
	s_mul_i32 s42, s13, 0x9000
	s_lshl_b32 s101, s27, 1
	s_add_i32 s42, s42, s101
	s_add_i32 s8, s8, 0x2000
	s_add_u32 s10, s10, s42
	s_addc_u32 s11, s11, 0
	s_mov_b32 m0, s8
	s_add_i32 s8, s8, 0x2000
	global_load_lds_dwordx4 v254, s[10:11]
	s_mov_b32 m0, s8
	s_add_u32 s10, s10, 0x240000
	s_addc_u32 s11, s11, 0
	global_load_lds_dwordx4 v254, s[10:11]
	s_add_i32 s98, s98, 0x8000
	s_cmp_eq_u32 s98, 0x19000
	s_cselect_b32 s98, 0x1000, s98
	s_mov_b32 s9, 1
	s_sub_i32 s27, s9, s78
	s_lshr_b32 s42, s23, 9
	s_lshl_b32 s101, s42, 2
	s_add_i32 s27, s27, s101
	s_add_i32 s27, s27, 0x100
	s_lshl_b32 s42, s42, 5
	s_add_i32 s42, s42, s32
	s_add_i32 s42, s42, s9
	s_cmp_lt_u32 s9, s78
	s_cselect_b32 s27, s42, s27
	s_lshl_b32 s27, s27, 6
	s_mul_i32 s42, s27, s37
	s_add_u32 s10, s50, s42
	s_addc_u32 s11, s51, 0
	s_lshl_b32 s101, s13, 1
	s_add_i32 s101, s101, 0x2800
	s_add_u32 s10, s10, s101
	s_addc_u32 s11, s11, 0
	s_lshl_b32 s8, s12, 10
	s_add_i32 s8, s8, s98
	s_mov_b32 m0, s8
	s_add_i32 s8, s8, 0x2000
	global_load_lds_dwordx4 v229, s[10:11]
	s_mov_b32 m0, s8
	s_add_u32 s10, s10, 0xd0000
	s_addc_u32 s11, s11, 0
	global_load_lds_dwordx4 v229, s[10:11]
	v_readlane_b32 s10, v252, 55
	v_readlane_b32 s11, v252, 56
	s_mul_i32 s42, s13, 0x9000
	s_lshl_b32 s101, s27, 1
	s_add_i32 s42, s42, s101
	s_add_i32 s8, s8, 0x2000
	s_add_u32 s10, s10, s42
	s_addc_u32 s11, s11, 0
	s_mov_b32 m0, s8
	s_add_i32 s8, s8, 0x2000
	global_load_lds_dwordx4 v254, s[10:11]
	s_mov_b32 m0, s8
	s_add_u32 s10, s10, 0x240000
	s_addc_u32 s11, s11, 0
	global_load_lds_dwordx4 v254, s[10:11]
	s_add_i32 s98, s98, 0x8000
	s_cmp_eq_u32 s98, 0x19000
	s_cselect_b32 s98, 0x1000, s98
	s_and_b32 s27, s23, 3
	s_lshl_b32 s27, s27, 4
	s_sub_i32 s27, s27, 8
	s_max_i32 s27, s27, 0
	s_min_i32 s42, s27, 32
	s_lshr_b32 s101, s42, 3
	v_lshrrev_b32_e32 v242, 2, v192
	v_and_b32_e32 v243, 3, v192
	v_lshl_add_u32 v244, v242, 3, v243
	v_add_u32_e32 v245, s42, v244
	v_add_u32_e32 v246, s101, v242
	v_and_b32_e32 v246, 1, v246
	v_lshl_or_b32 v246, v246, 2, v243
	v_lshrrev_b32_e32 v247, 2, v197
	v_lshl_add_u32 v246, v246, 1, v247
	v_and_b32_e32 v246, 15, v246
	v_lshlrev_b32_e32 v246, 4, v246
	v_lshl_add_u32 v255, v245, 8, v246
	v_and_b32_e32 v246, 1, v242
	v_lshl_or_b32 v246, v246, 2, v243
	v_lshl_add_u32 v246, v246, 1, v247
	v_and_b32_e32 v246, 15, v246
	v_lshlrev_b32_e32 v246, 4, v246
	v_lshl_add_u32 v190, v244, 8, v246
	v_and_b32_e32 v242, 14, v192
	v_add_u32_e32 v242, v242, v247
	v_lshlrev_b32_e32 v243, 7, v192
	v_add_u32_e32 v243, 0x4000, v243
	v_add_u32_e32 v244, s101, v242
	v_and_b32_e32 v244, 7, v244
	v_lshl_add_u32 v191, v244, 4, v243
	v_and_b32_e32 v244, 7, v242
	v_lshl_add_u32 v181, v244, 4, v243
	v_add_u32_e32 v244, 4, v242
	v_and_b32_e32 v244, 7, v244
	v_lshl_add_u32 v249, v244, 4, v243
	global_load_dwordx4 v[146:149], v[2:3], off
	global_load_dwordx4 v[150:153], v[2:3], off offset:64
	global_load_dwordx4 v[154:157], v[2:3], off offset:128
	global_load_dwordx4 v[158:161], v[2:3], off offset:192
	global_load_dwordx4 v[98:101], v[4:5], off
	global_load_dwordx4 v[102:105], v[4:5], off offset:64
	global_load_dwordx4 v[106:109], v[4:5], off offset:128
	global_load_dwordx4 v[110:113], v[4:5], off offset:192
	global_load_dwordx4 v[114:117], v[176:177], off
	global_load_dwordx4 v[118:121], v[176:177], off offset:16
	global_load_dwordx4 v[122:125], v[176:177], off offset:128
	global_load_dwordx4 v[126:129], v[176:177], off offset:144
	global_load_dwordx4 v[130:133], v[176:177], off offset:256
	global_load_dwordx4 v[134:137], v[176:177], off offset:272
	global_load_dwordx4 v[138:141], v[176:177], off offset:384
	global_load_dwordx4 v[142:145], v[176:177], off offset:400
	s_waitcnt vmcnt(8)
	v_lshlrev_b32_e32 v8, 16, v146
	v_lshlrev_b32_e32 v9, 16, v98
	v_and_b32_e32 v10, 0xffff0000, v146
	v_and_b32_e32 v11, 0xffff0000, v98
	v_mul_f32_e32 v6, v8, v8
	v_mul_f32_e32 v7, v9, v9
	v_fmac_f32_e32 v6, v10, v10
	v_fmac_f32_e32 v7, v11, v11
	v_lshlrev_b32_e32 v8, 16, v147
	v_lshlrev_b32_e32 v9, 16, v99
	v_and_b32_e32 v10, 0xffff0000, v147
	v_and_b32_e32 v11, 0xffff0000, v99
	v_fmac_f32_e32 v6, v8, v8
	v_fmac_f32_e32 v7, v9, v9
	v_fmac_f32_e32 v6, v10, v10
	v_fmac_f32_e32 v7, v11, v11
	v_lshlrev_b32_e32 v8, 16, v148
	v_lshlrev_b32_e32 v9, 16, v100
	v_and_b32_e32 v10, 0xffff0000, v148
	v_and_b32_e32 v11, 0xffff0000, v100
	v_fmac_f32_e32 v6, v8, v8
	v_fmac_f32_e32 v7, v9, v9
	v_fmac_f32_e32 v6, v10, v10
	v_fmac_f32_e32 v7, v11, v11
	v_lshlrev_b32_e32 v8, 16, v149
	v_lshlrev_b32_e32 v9, 16, v101
	v_and_b32_e32 v10, 0xffff0000, v149
	v_and_b32_e32 v11, 0xffff0000, v101
	v_fmac_f32_e32 v6, v8, v8
	v_fmac_f32_e32 v7, v9, v9
	v_fmac_f32_e32 v6, v10, v10
	v_fmac_f32_e32 v7, v11, v11
	v_lshlrev_b32_e32 v8, 16, v150
	v_lshlrev_b32_e32 v9, 16, v102
	v_and_b32_e32 v10, 0xffff0000, v150
	v_and_b32_e32 v11, 0xffff0000, v102
	v_fmac_f32_e32 v6, v8, v8
	v_fmac_f32_e32 v7, v9, v9
	v_fmac_f32_e32 v6, v10, v10
	v_fmac_f32_e32 v7, v11, v11
	v_lshlrev_b32_e32 v8, 16, v151
	v_lshlrev_b32_e32 v9, 16, v103
	v_and_b32_e32 v10, 0xffff0000, v151
	v_and_b32_e32 v11, 0xffff0000, v103
	v_fmac_f32_e32 v6, v8, v8
	v_fmac_f32_e32 v7, v9, v9
	v_fmac_f32_e32 v6, v10, v10
	v_fmac_f32_e32 v7, v11, v11
	v_lshlrev_b32_e32 v8, 16, v152
	v_lshlrev_b32_e32 v9, 16, v104
	v_and_b32_e32 v10, 0xffff0000, v152
	v_and_b32_e32 v11, 0xffff0000, v104
	v_fmac_f32_e32 v6, v8, v8
	v_fmac_f32_e32 v7, v9, v9
	v_fmac_f32_e32 v6, v10, v10
	v_fmac_f32_e32 v7, v11, v11
	v_lshlrev_b32_e32 v8, 16, v153
	v_lshlrev_b32_e32 v9, 16, v105
	v_and_b32_e32 v10, 0xffff0000, v153
	v_and_b32_e32 v11, 0xffff0000, v105
	v_fmac_f32_e32 v6, v8, v8
	v_fmac_f32_e32 v7, v9, v9
	v_fmac_f32_e32 v6, v10, v10
	v_fmac_f32_e32 v7, v11, v11
	v_lshlrev_b32_e32 v8, 16, v154
	v_lshlrev_b32_e32 v9, 16, v106
	v_and_b32_e32 v10, 0xffff0000, v154
	v_and_b32_e32 v11, 0xffff0000, v106
	v_fmac_f32_e32 v6, v8, v8
	v_fmac_f32_e32 v7, v9, v9
	v_fmac_f32_e32 v6, v10, v10
	v_fmac_f32_e32 v7, v11, v11
	v_lshlrev_b32_e32 v8, 16, v155
	v_lshlrev_b32_e32 v9, 16, v107
	v_and_b32_e32 v10, 0xffff0000, v155
	v_and_b32_e32 v11, 0xffff0000, v107
	v_fmac_f32_e32 v6, v8, v8
	v_fmac_f32_e32 v7, v9, v9
	v_fmac_f32_e32 v6, v10, v10
	v_fmac_f32_e32 v7, v11, v11
	v_lshlrev_b32_e32 v8, 16, v156
	v_lshlrev_b32_e32 v9, 16, v108
	v_and_b32_e32 v10, 0xffff0000, v156
	v_and_b32_e32 v11, 0xffff0000, v108
	v_fmac_f32_e32 v6, v8, v8
	v_fmac_f32_e32 v7, v9, v9
	v_fmac_f32_e32 v6, v10, v10
	v_fmac_f32_e32 v7, v11, v11
	v_lshlrev_b32_e32 v8, 16, v157
	v_lshlrev_b32_e32 v9, 16, v109
	v_and_b32_e32 v10, 0xffff0000, v157
	v_and_b32_e32 v11, 0xffff0000, v109
	v_fmac_f32_e32 v6, v8, v8
	v_fmac_f32_e32 v7, v9, v9
	v_fmac_f32_e32 v6, v10, v10
	v_fmac_f32_e32 v7, v11, v11
	v_lshlrev_b32_e32 v8, 16, v158
	v_lshlrev_b32_e32 v9, 16, v110
	v_and_b32_e32 v10, 0xffff0000, v158
	v_and_b32_e32 v11, 0xffff0000, v110
	v_fmac_f32_e32 v6, v8, v8
	v_fmac_f32_e32 v7, v9, v9
	v_fmac_f32_e32 v6, v10, v10
	v_fmac_f32_e32 v7, v11, v11
	v_lshlrev_b32_e32 v8, 16, v159
	v_lshlrev_b32_e32 v9, 16, v111
	v_and_b32_e32 v10, 0xffff0000, v159
	v_and_b32_e32 v11, 0xffff0000, v111
	v_fmac_f32_e32 v6, v8, v8
	v_fmac_f32_e32 v7, v9, v9
	v_fmac_f32_e32 v6, v10, v10
	v_fmac_f32_e32 v7, v11, v11
	v_lshlrev_b32_e32 v8, 16, v160
	v_lshlrev_b32_e32 v9, 16, v112
	v_and_b32_e32 v10, 0xffff0000, v160
	v_and_b32_e32 v11, 0xffff0000, v112
	v_fmac_f32_e32 v6, v8, v8
	v_fmac_f32_e32 v7, v9, v9
	v_fmac_f32_e32 v6, v10, v10
	v_fmac_f32_e32 v7, v11, v11
	v_lshlrev_b32_e32 v8, 16, v161
	v_lshlrev_b32_e32 v9, 16, v113
	v_and_b32_e32 v10, 0xffff0000, v161
	v_and_b32_e32 v11, 0xffff0000, v113
	v_fmac_f32_e32 v6, v8, v8
	v_fmac_f32_e32 v7, v9, v9
	v_fmac_f32_e32 v6, v10, v10
	v_fmac_f32_e32 v7, v11, v11
	ds_bpermute_b32 v8, v171, v6
	ds_bpermute_b32 v9, v171, v7
	s_waitcnt lgkmcnt(0)
	v_add_f32_e32 v6, v6, v8
	v_add_f32_e32 v7, v7, v9
	ds_bpermute_b32 v8, v199, v6
	ds_bpermute_b32 v9, v199, v7
	s_waitcnt lgkmcnt(0)
	v_add_f32_e32 v6, v6, v8
	v_add_f32_e32 v7, v7, v9
	v_fmamk_f32 v6, v6, 0x3c000000, v230
	v_mul_f32_e32 v8, 0x4b800000, v6
	v_cmp_gt_f32_e32 vcc, s70, v6
	s_nop 1
	v_cndmask_b32_e32 v6, v6, v8, vcc
	v_rsq_f32_e32 v14, v6
	s_nop 0
	v_mul_f32_e32 v8, 0x45800000, v14
	v_cndmask_b32_e32 v14, v14, v8, vcc
	v_mul_f32_e32 v14, 0x3db504f3, v14
	v_fmamk_f32 v7, v7, 0x3c000000, v230
	v_mul_f32_e32 v9, 0x4b800000, v7
	v_cmp_gt_f32_e32 vcc, s70, v7
	s_nop 1
	v_cndmask_b32_e32 v7, v7, v9, vcc
	v_rsq_f32_e32 v15, v7
	s_nop 0
	v_mul_f32_e32 v9, 0x45800000, v15
	v_cndmask_b32_e32 v15, v15, v9, vcc
	v_mul_f32_e32 v15, 0x3db504f3, v15
	s_waitcnt vmcnt(0)
	v_or_b32_e32 v242, v172, v192
	s_lshl_b32 s27, s12, 6
	v_add_u32_e32 v242, s27, v242
	v_lshlrev_b32_e32 v242, 2, v242
	ds_write_b32 v242, v248
	s_waitcnt lgkmcnt(0)
	v_lshlrev_b32_e32 v16, 16, v146
	v_and_b32_e32 v17, 0xffff0000, v146
	v_mul_f32_e32 v16, v14, v16
	v_mul_f32_e32 v17, v14, v17
	v_mul_f32_e32 v16, v114, v16
	v_mul_f32_e32 v17, v115, v17
	v_cvt_pk_bf16_f32 v50, v16, v17
	v_lshlrev_b32_e32 v16, 16, v147
	v_and_b32_e32 v17, 0xffff0000, v147
	v_mul_f32_e32 v16, v14, v16
	v_mul_f32_e32 v17, v14, v17
	v_mul_f32_e32 v16, v116, v16
	v_mul_f32_e32 v17, v117, v17
	v_cvt_pk_bf16_f32 v51, v16, v17
	v_lshlrev_b32_e32 v16, 16, v148
	v_and_b32_e32 v17, 0xffff0000, v148
	v_mul_f32_e32 v16, v14, v16
	v_mul_f32_e32 v17, v14, v17
	v_mul_f32_e32 v16, v118, v16
	v_mul_f32_e32 v17, v119, v17
	v_cvt_pk_bf16_f32 v52, v16, v17
	v_lshlrev_b32_e32 v16, 16, v149
	v_and_b32_e32 v17, 0xffff0000, v149
	v_mul_f32_e32 v16, v14, v16
	v_mul_f32_e32 v17, v14, v17
	v_mul_f32_e32 v16, v120, v16
	v_mul_f32_e32 v17, v121, v17
	v_cvt_pk_bf16_f32 v53, v16, v17
	v_lshlrev_b32_e32 v16, 16, v98
	v_and_b32_e32 v17, 0xffff0000, v98
	v_mul_f32_e32 v16, v15, v16
	v_mul_f32_e32 v17, v15, v17
	v_mul_f32_e32 v16, v114, v16
	v_mul_f32_e32 v17, v115, v17
	v_cvt_pk_bf16_f32 v78, v16, v17
	v_lshlrev_b32_e32 v16, 16, v99
	v_and_b32_e32 v17, 0xffff0000, v99
	v_mul_f32_e32 v16, v15, v16
	v_mul_f32_e32 v17, v15, v17
	v_mul_f32_e32 v16, v116, v16
	v_mul_f32_e32 v17, v117, v17
	v_cvt_pk_bf16_f32 v79, v16, v17
	v_lshlrev_b32_e32 v16, 16, v100
	v_and_b32_e32 v17, 0xffff0000, v100
	v_mul_f32_e32 v16, v15, v16
	v_mul_f32_e32 v17, v15, v17
	v_mul_f32_e32 v16, v118, v16
	v_mul_f32_e32 v17, v119, v17
	v_cvt_pk_bf16_f32 v80, v16, v17
	v_lshlrev_b32_e32 v16, 16, v101
	v_and_b32_e32 v17, 0xffff0000, v101
	v_mul_f32_e32 v16, v15, v16
	v_mul_f32_e32 v17, v15, v17
	v_mul_f32_e32 v16, v120, v16
	v_mul_f32_e32 v17, v121, v17
	v_cvt_pk_bf16_f32 v81, v16, v17
	v_lshlrev_b32_e32 v16, 16, v150
	v_and_b32_e32 v17, 0xffff0000, v150
	v_mul_f32_e32 v16, v14, v16
	v_mul_f32_e32 v17, v14, v17
	v_mul_f32_e32 v16, v122, v16
	v_mul_f32_e32 v17, v123, v17
	v_cvt_pk_bf16_f32 v54, v16, v17
	v_lshlrev_b32_e32 v16, 16, v151
	v_and_b32_e32 v17, 0xffff0000, v151
	v_mul_f32_e32 v16, v14, v16
	v_mul_f32_e32 v17, v14, v17
	v_mul_f32_e32 v16, v124, v16
	v_mul_f32_e32 v17, v125, v17
	v_cvt_pk_bf16_f32 v55, v16, v17
	v_lshlrev_b32_e32 v16, 16, v152
	v_and_b32_e32 v17, 0xffff0000, v152
	v_mul_f32_e32 v16, v14, v16
	v_mul_f32_e32 v17, v14, v17
	v_mul_f32_e32 v16, v126, v16
	v_mul_f32_e32 v17, v127, v17
	v_cvt_pk_bf16_f32 v56, v16, v17
	v_lshlrev_b32_e32 v16, 16, v153
	v_and_b32_e32 v17, 0xffff0000, v153
	v_mul_f32_e32 v16, v14, v16
	v_mul_f32_e32 v17, v14, v17
	v_mul_f32_e32 v16, v128, v16
	v_mul_f32_e32 v17, v129, v17
	v_cvt_pk_bf16_f32 v57, v16, v17
	v_lshlrev_b32_e32 v16, 16, v102
	v_and_b32_e32 v17, 0xffff0000, v102
	v_mul_f32_e32 v16, v15, v16
	v_mul_f32_e32 v17, v15, v17
	v_mul_f32_e32 v16, v122, v16
	v_mul_f32_e32 v17, v123, v17
	v_cvt_pk_bf16_f32 v82, v16, v17
	v_lshlrev_b32_e32 v16, 16, v103
	v_and_b32_e32 v17, 0xffff0000, v103
	v_mul_f32_e32 v16, v15, v16
	v_mul_f32_e32 v17, v15, v17
	v_mul_f32_e32 v16, v124, v16
	v_mul_f32_e32 v17, v125, v17
	v_cvt_pk_bf16_f32 v83, v16, v17
	v_lshlrev_b32_e32 v16, 16, v104
	v_and_b32_e32 v17, 0xffff0000, v104
	v_mul_f32_e32 v16, v15, v16
	v_mul_f32_e32 v17, v15, v17
	v_mul_f32_e32 v16, v126, v16
	v_mul_f32_e32 v17, v127, v17
	v_cvt_pk_bf16_f32 v84, v16, v17
	v_lshlrev_b32_e32 v16, 16, v105
	v_and_b32_e32 v17, 0xffff0000, v105
	v_mul_f32_e32 v16, v15, v16
	v_mul_f32_e32 v17, v15, v17
	v_mul_f32_e32 v16, v128, v16
	v_mul_f32_e32 v17, v129, v17
	v_cvt_pk_bf16_f32 v85, v16, v17
	v_lshlrev_b32_e32 v16, 16, v154
	v_and_b32_e32 v17, 0xffff0000, v154
	v_mul_f32_e32 v16, v14, v16
	v_mul_f32_e32 v17, v14, v17
	v_mul_f32_e32 v16, v130, v16
	v_mul_f32_e32 v17, v131, v17
	v_cvt_pk_bf16_f32 v58, v16, v17
	v_lshlrev_b32_e32 v16, 16, v155
	v_and_b32_e32 v17, 0xffff0000, v155
	v_mul_f32_e32 v16, v14, v16
	v_mul_f32_e32 v17, v14, v17
	v_mul_f32_e32 v16, v132, v16
	v_mul_f32_e32 v17, v133, v17
	v_cvt_pk_bf16_f32 v59, v16, v17
	v_lshlrev_b32_e32 v16, 16, v156
	v_and_b32_e32 v17, 0xffff0000, v156
	v_mul_f32_e32 v16, v14, v16
	v_mul_f32_e32 v17, v14, v17
	v_mul_f32_e32 v16, v134, v16
	v_mul_f32_e32 v17, v135, v17
	v_cvt_pk_bf16_f32 v60, v16, v17
	v_lshlrev_b32_e32 v16, 16, v157
	v_and_b32_e32 v17, 0xffff0000, v157
	v_mul_f32_e32 v16, v14, v16
	v_mul_f32_e32 v17, v14, v17
	v_mul_f32_e32 v16, v136, v16
	v_mul_f32_e32 v17, v137, v17
	v_cvt_pk_bf16_f32 v61, v16, v17
	v_lshlrev_b32_e32 v16, 16, v106
	v_and_b32_e32 v17, 0xffff0000, v106
	v_mul_f32_e32 v16, v15, v16
	v_mul_f32_e32 v17, v15, v17
	v_mul_f32_e32 v16, v130, v16
	v_mul_f32_e32 v17, v131, v17
	v_cvt_pk_bf16_f32 v86, v16, v17
	v_lshlrev_b32_e32 v16, 16, v107
	v_and_b32_e32 v17, 0xffff0000, v107
	v_mul_f32_e32 v16, v15, v16
	v_mul_f32_e32 v17, v15, v17
	v_mul_f32_e32 v16, v132, v16
	v_mul_f32_e32 v17, v133, v17
	v_cvt_pk_bf16_f32 v87, v16, v17
	v_lshlrev_b32_e32 v16, 16, v108
	v_and_b32_e32 v17, 0xffff0000, v108
	v_mul_f32_e32 v16, v15, v16
	v_mul_f32_e32 v17, v15, v17
	v_mul_f32_e32 v16, v134, v16
	v_mul_f32_e32 v17, v135, v17
	v_cvt_pk_bf16_f32 v88, v16, v17
	v_lshlrev_b32_e32 v16, 16, v109
	v_and_b32_e32 v17, 0xffff0000, v109
	v_mul_f32_e32 v16, v15, v16
	v_mul_f32_e32 v17, v15, v17
	v_mul_f32_e32 v16, v136, v16
	v_mul_f32_e32 v17, v137, v17
	v_cvt_pk_bf16_f32 v89, v16, v17
	v_lshlrev_b32_e32 v16, 16, v158
	v_and_b32_e32 v17, 0xffff0000, v158
	v_mul_f32_e32 v16, v14, v16
	v_mul_f32_e32 v17, v14, v17
	v_mul_f32_e32 v16, v138, v16
	v_mul_f32_e32 v17, v139, v17
	v_cvt_pk_bf16_f32 v66, v16, v17
	v_lshlrev_b32_e32 v16, 16, v159
	v_and_b32_e32 v17, 0xffff0000, v159
	v_mul_f32_e32 v16, v14, v16
	v_mul_f32_e32 v17, v14, v17
	v_mul_f32_e32 v16, v140, v16
	v_mul_f32_e32 v17, v141, v17
	v_cvt_pk_bf16_f32 v67, v16, v17
	v_lshlrev_b32_e32 v16, 16, v160
	v_and_b32_e32 v17, 0xffff0000, v160
	v_mul_f32_e32 v16, v14, v16
	v_mul_f32_e32 v17, v14, v17
	v_mul_f32_e32 v16, v142, v16
	v_mul_f32_e32 v17, v143, v17
	v_cvt_pk_bf16_f32 v68, v16, v17
	v_lshlrev_b32_e32 v16, 16, v161
	v_and_b32_e32 v17, 0xffff0000, v161
	v_mul_f32_e32 v16, v14, v16
	v_mul_f32_e32 v17, v14, v17
	v_mul_f32_e32 v16, v144, v16
	v_mul_f32_e32 v17, v145, v17
	v_cvt_pk_bf16_f32 v69, v16, v17
	v_lshlrev_b32_e32 v16, 16, v110
	v_and_b32_e32 v17, 0xffff0000, v110
	v_mul_f32_e32 v16, v15, v16
	v_mul_f32_e32 v17, v15, v17
	v_mul_f32_e32 v16, v138, v16
	v_mul_f32_e32 v17, v139, v17
	v_cvt_pk_bf16_f32 v94, v16, v17
	v_lshlrev_b32_e32 v16, 16, v111
	v_and_b32_e32 v17, 0xffff0000, v111
	v_mul_f32_e32 v16, v15, v16
	v_mul_f32_e32 v17, v15, v17
	v_mul_f32_e32 v16, v140, v16
	v_mul_f32_e32 v17, v141, v17
	v_cvt_pk_bf16_f32 v95, v16, v17
	v_lshlrev_b32_e32 v16, 16, v112
	v_and_b32_e32 v17, 0xffff0000, v112
	v_mul_f32_e32 v16, v15, v16
	v_mul_f32_e32 v17, v15, v17
	v_mul_f32_e32 v16, v142, v16
	v_mul_f32_e32 v17, v143, v17
	v_cvt_pk_bf16_f32 v96, v16, v17
	v_lshlrev_b32_e32 v16, 16, v113
	v_and_b32_e32 v17, 0xffff0000, v113
	v_mul_f32_e32 v16, v15, v16
	v_mul_f32_e32 v17, v15, v17
	v_mul_f32_e32 v16, v144, v16
	v_mul_f32_e32 v17, v145, v17
	v_cvt_pk_bf16_f32 v97, v16, v17
	s_bfe_u32 s6, s23, 0x40002
	s_lshl_b32 s7, s6, 1
	v_sub_u32_e64 v2, s7, 4 clamp
	s_and_b32 s10, s26, 48
	v_readfirstlane_b32 s8, v2
	v_sub_u32_e64 v2, s7, 3 clamp
	s_min_u32 s3, s8, 24
	v_readfirstlane_b32 s7, v2
	v_sub_u32_e64 v2, s10, 8 clamp
	v_min_u32_e32 v2, 32, v2
	s_mul_i32 s11, s3, 31
	v_add_u32_e32 v2, s11, v2
	v_add_u32_e32 v2, v2, v173
	v_subrev_u32_e32 v2, s10, v2
	s_mul_i32 s6, s6, 62
	v_subrev_u32_e32 v188, s6, v2
	v_lshlrev_b32_e32 v188, 2, v188
	v_sub_u32_e64 v2, s1, 8 clamp
	s_min_u32 s7, s7, 24
	v_min_u32_e32 v4, 32, v2
	v_or_b32_e32 v2, s1, v192
	s_sub_i32 s6, s7, s3
	v_sub_u32_e64 v2, v2, 8 clamp
	s_add_i32 s6, s6, 15
	s_or_b32 s0, s0, s17
	v_min_u32_e32 v5, 48, v2
	v_or_b32_e32 v2, s13, v192
	s_mul_i32 s42, s0, 0x1d1
	v_readlane_b32 s52, v252, 12
	v_mul_u32_u24_e32 v2, 0x4800, v2
	s_lshl_b32 s8, s3, 5
	s_lshl_b32 s9, s7, 5
	s_lshl_b64 s[0:1], s[42:43], 2
	v_readlane_b32 s64, v252, 24
	v_lshlrev_b32_e32 v2, 1, v2
	v_mov_b32_e32 v3, v195
	v_readlane_b32 s65, v252, 25
	s_add_u32 s0, s64, s0
	v_add_u32_e32 v2, v4, v170
	v_add_u32_e32 v3, 16, v5
	s_addc_u32 s1, s65, s1
	s_lshl_b32 s10, s4, 8
	v_cmp_ge_u32_e32 vcc, v2, v5
	v_cmp_lt_u32_e64 s[4:5], v2, v3
	v_or_b32_e32 v4, 1, v2
	v_readlane_b32 s53, v252, 13
	s_and_b64 s[40:41], vcc, s[4:5]
	v_cmp_ge_u32_e32 vcc, v4, v5
	v_cmp_lt_u32_e64 s[4:5], v4, v3
	v_or_b32_e32 v4, 2, v2
	v_readlane_b32 s54, v252, 14
	v_readlane_b32 s55, v252, 15
	s_and_b64 s[52:53], vcc, s[4:5]
	v_cmp_ge_u32_e32 vcc, v4, v5
	v_cmp_lt_u32_e64 s[4:5], v4, v3
	v_or_b32_e32 v4, 3, v2
	v_readlane_b32 s60, v252, 20
	v_readlane_b32 s61, v252, 21
	s_and_b64 s[54:55], vcc, s[4:5]
	v_cmp_ge_u32_e32 vcc, v4, v5
	v_cmp_lt_u32_e64 s[4:5], v4, v3
	v_or_b32_e32 v4, 4, v2
	v_readlane_b32 s62, v252, 22
	v_readlane_b32 s63, v252, 23
	s_and_b64 s[60:61], vcc, s[4:5]
	v_cmp_ge_u32_e32 vcc, v4, v5
	v_cmp_lt_u32_e64 s[4:5], v4, v3
	v_or_b32_e32 v4, 5, v2
	s_and_b64 s[62:63], vcc, s[4:5]
	v_cmp_ge_u32_e32 vcc, v4, v5
	v_cmp_lt_u32_e64 s[4:5], v4, v3
	v_or_b32_e32 v4, 6, v2
	s_and_b64 s[80:81], vcc, s[4:5]
	v_cmp_ge_u32_e32 vcc, v4, v5
	v_cmp_lt_u32_e64 s[4:5], v4, v3
	v_or_b32_e32 v2, 7, v2
	s_and_b64 s[82:83], vcc, s[4:5]
	v_cmp_ge_u32_e32 vcc, v2, v5
	v_cmp_lt_u32_e64 s[4:5], v2, v3
	s_add_i32 s10, s10, s8
	s_and_b64 s[6:7], vcc, s[4:5]
	s_sub_i32 s4, s10, s9
	v_mov_b32_e32 v175, 0
	s_mov_b32 s70, 0
	v_mov_b32_e32 v253, 0xff800000
	s_movk_i32 s22, 0x740
	v_mov_b32_e32 v185, 0xff800000
	v_mov_b32_e32 v203, 0xff800000
	v_mov_b32_e32 v201, 0
	v_mov_b32_e32 v34, 0
	v_mov_b32_e32 v35, v175
	v_mov_b32_e32 v36, v175
	v_mov_b32_e32 v37, v175
	v_mov_b32_e32 v38, 0
	v_mov_b32_e32 v39, v175
	v_mov_b32_e32 v40, v175
	v_mov_b32_e32 v41, v175
	v_mov_b32_e32 v42, 0
	v_mov_b32_e32 v43, v175
	v_mov_b32_e32 v44, v175
	v_mov_b32_e32 v45, v175
	v_mov_b32_e32 v46, 0
	v_mov_b32_e32 v47, v175
	v_mov_b32_e32 v48, v175
	v_mov_b32_e32 v49, v175
	v_mov_b32_e32 v62, 0
	v_mov_b32_e32 v63, v175
	v_mov_b32_e32 v64, v175
	v_mov_b32_e32 v65, v175
	v_mov_b32_e32 v70, 0
	v_mov_b32_e32 v71, v175
	v_mov_b32_e32 v72, v175
	v_mov_b32_e32 v73, v175
	v_mov_b32_e32 v74, 0
	v_mov_b32_e32 v75, v175
	v_mov_b32_e32 v76, v175
	v_mov_b32_e32 v77, v175
	v_mov_b32_e32 v90, 0
	v_mov_b32_e32 v91, v175
	v_mov_b32_e32 v92, v175
	v_mov_b32_e32 v93, v175
	v_mov_b32_e32 v30, 0
	v_mov_b32_e32 v31, v175
	v_mov_b32_e32 v32, v175
	v_mov_b32_e32 v33, v175
	v_mov_b32_e32 v26, 0
	v_mov_b32_e32 v27, v175
	v_mov_b32_e32 v28, v175
	v_mov_b32_e32 v29, v175
	v_mov_b32_e32 v22, 0
	v_mov_b32_e32 v23, v175
	v_mov_b32_e32 v24, v175
	v_mov_b32_e32 v25, v175
	v_mov_b32_e32 v18, 0
	v_mov_b32_e32 v19, v175
	v_mov_b32_e32 v20, v175
	v_mov_b32_e32 v21, v175
	v_mov_b32_e32 v14, 0
	v_mov_b32_e32 v15, v175
	v_mov_b32_e32 v16, v175
	v_mov_b32_e32 v17, v175
	v_mov_b32_e32 v10, 0
	v_mov_b32_e32 v11, v175
	v_mov_b32_e32 v12, v175
	v_mov_b32_e32 v13, v175
	v_mov_b32_e32 v6, 0
	v_mov_b32_e32 v7, v175
	v_mov_b32_e32 v8, v175
	v_mov_b32_e32 v9, v175
	v_mov_b32_e32 v2, 0
	v_mov_b32_e32 v3, v175
	v_mov_b32_e32 v4, v175
	v_mov_b32_e32 v5, v175
	v_readlane_b32 s56, v252, 16
	v_readlane_b32 s57, v252, 17
	v_readlane_b32 s58, v252, 18
	v_readlane_b32 s59, v252, 19
	v_readlane_b32 s66, v252, 26
	v_readlane_b32 s67, v252, 27

.Lat_wdone:
	s_barrier
	s_cmp_lt_u32 s71, s78
	s_cbranch_scc0 .Lat_ctx_tile
	s_add_i32 s27, s32, s71
	s_sub_i32 s70, s27, s15
	s_cmp_lt_u32 s70, s2
	s_cselect_b32 s100, 1, 0
	s_cbranch_scc0 .Lat_loc_dma
	v_add_u32_e32 v247, 32, v188
	v_med3_i32 v247, v247, 0, s22
	ds_read_b32 v213, v247
	v_add_u32_e32 v248, 36, v188
	v_med3_i32 v248, v248, 0, s22
	ds_read_b32 v214, v248
	v_add_u32_e32 v247, 40, v188
	v_med3_i32 v247, v247, 0, s22
	ds_read_b32 v215, v247
	v_add_u32_e32 v248, 44, v188
	v_med3_i32 v248, v248, 0, s22
	ds_read_b32 v216, v248
	v_add_u32_e32 v247, 48, v188
	v_med3_i32 v247, v247, 0, s22
	ds_read_b32 v217, v247
	v_add_u32_e32 v248, 52, v188
	v_med3_i32 v248, v248, 0, s22
	ds_read_b32 v218, v248
	v_add_u32_e32 v247, 56, v188
	v_med3_i32 v247, v247, 0, s22
	ds_read_b32 v219, v247
	v_add_u32_e32 v248, 60, v188
	v_med3_i32 v248, v248, 0, s22
	ds_read_b32 v220, v248
	v_subrev_u32_e32 v247, 92, v188
	v_med3_i32 v247, v247, 0, s22
	ds_read_b32 v221, v247
	v_subrev_u32_e32 v248, 88, v188
	v_med3_i32 v248, v248, 0, s22
	ds_read_b32 v222, v248
	v_subrev_u32_e32 v247, 84, v188
	v_med3_i32 v247, v247, 0, s22
	ds_read_b32 v223, v247
	v_subrev_u32_e32 v248, 80, v188
	v_med3_i32 v248, v248, 0, s22
	ds_read_b32 v224, v248
	v_subrev_u32_e32 v247, 76, v188
	v_med3_i32 v247, v247, 0, s22
	ds_read_b32 v225, v247
	v_subrev_u32_e32 v248, 72, v188
	v_med3_i32 v248, v248, 0, s22
	ds_read_b32 v226, v248
	v_subrev_u32_e32 v247, 68, v188
	v_med3_i32 v247, v247, 0, s22
	ds_read_b32 v227, v247
	v_subrev_u32_e32 v248, 64, v188
	v_med3_i32 v248, v248, 0, s22
	ds_read_b32 v228, v248
.Lat_loc_dma:
	s_add_i32 s9, s71, 2
	s_sub_i32 s27, s9, s78
	s_lshr_b32 s42, s23, 9
	s_lshl_b32 s101, s42, 2
	s_add_i32 s27, s27, s101
	s_add_i32 s27, s27, 0x100
	s_lshl_b32 s42, s42, 5
	s_add_i32 s42, s42, s32
	s_add_i32 s42, s42, s9
	s_cmp_lt_u32 s9, s78
	s_cselect_b32 s27, s42, s27
	s_lshl_b32 s27, s27, 6
	s_mul_i32 s42, s27, s37
	s_add_u32 s10, s50, s42
	s_addc_u32 s11, s51, 0
	s_lshl_b32 s101, s13, 1
	s_add_i32 s101, s101, 0x2800
	s_add_u32 s10, s10, s101
	s_addc_u32 s11, s11, 0
	s_lshl_b32 s8, s12, 10
	s_add_i32 s8, s8, s98
	s_mov_b32 m0, s8
	s_add_i32 s8, s8, 0x2000
	global_load_lds_dwordx4 v229, s[10:11]
	s_mov_b32 m0, s8
	s_add_u32 s10, s10, 0xd0000
	s_addc_u32 s11, s11, 0
	global_load_lds_dwordx4 v229, s[10:11]
	v_readlane_b32 s10, v252, 55
	v_readlane_b32 s11, v252, 56
	s_mul_i32 s42, s13, 0x9000
	s_lshl_b32 s101, s27, 1
	s_add_i32 s42, s42, s101
	s_add_i32 s8, s8, 0x2000
	s_add_u32 s10, s10, s42
	s_addc_u32 s11, s11, 0
	s_mov_b32 m0, s8
	s_add_i32 s8, s8, 0x2000
	global_load_lds_dwordx4 v254, s[10:11]
	s_mov_b32 m0, s8
	s_add_u32 s10, s10, 0x240000
	s_addc_u32 s11, s11, 0
	global_load_lds_dwordx4 v254, s[10:11]
	s_add_i32 s98, s98, 0x8000
	s_cmp_eq_u32 s98, 0x19000
	s_cselect_b32 s98, 0x1000, s98
	s_cmp_eq_u32 s100, 0
	s_cbranch_scc1 .Lat_tile_next
	v_add_u32_e32 v242, s99, v255
	v_xor_b32_e32 v243, 64, v255
	v_xor_b32_e32 v244, 0x80, v255
	v_xor_b32_e32 v245, 0xc0, v255
	v_add_u32_e32 v243, s99, v243
	v_add_u32_e32 v244, s99, v244
	v_add_u32_e32 v245, s99, v245
	v_add_u32_e32 v246, s99, v191
	ds_read_b128 v[142:145], v242
	ds_read_b128 v[130:133], v243
	ds_read_b128 v[134:137], v244
	ds_read_b128 v[138:141], v245
	ds_read_b128 v[158:161], v242 offset:1024
	ds_read_b128 v[150:153], v243 offset:1024
	ds_read_b128 v[154:157], v244 offset:1024
	ds_read_b128 v[146:149], v245 offset:1024
	ds_read_b128 v[126:129], v246
	ds_read_b128 v[122:125], v246 offset:2048
	ds_read_b128 v[118:121], v246 offset:4096
	ds_read_b128 v[114:117], v246 offset:6144
	ds_read_b128 v[110:113], v246 offset:8192
	ds_read_b128 v[106:109], v246 offset:10240
	ds_read_b128 v[102:105], v246 offset:12288
	ds_read_b128 v[98:101], v246 offset:14336
	s_mov_b32 s100, 2
	s_branch .Lat_body
.Lat_ctx_tile:
	s_add_i32 s9, s71, 2
	s_add_i32 s42, s78, 4
	s_cmp_lt_u32 s9, s42
	s_cbranch_scc0 .Lat_ctx_nodma
	s_sub_i32 s27, s9, s78
	s_lshr_b32 s42, s23, 9
	s_lshl_b32 s101, s42, 2
	s_add_i32 s27, s27, s101
	s_add_i32 s27, s27, 0x100
	s_lshl_b32 s42, s42, 5
	s_add_i32 s42, s42, s32
	s_add_i32 s42, s42, s9
	s_cmp_lt_u32 s9, s78
	s_cselect_b32 s27, s42, s27
	s_lshl_b32 s27, s27, 6
	s_mul_i32 s42, s27, s37
	s_add_u32 s10, s50, s42
	s_addc_u32 s11, s51, 0
	s_lshl_b32 s101, s13, 1
	s_add_i32 s101, s101, 0x2800
	s_add_u32 s10, s10, s101
	s_addc_u32 s11, s11, 0
	s_lshl_b32 s8, s12, 10
	s_add_i32 s8, s8, s98
	s_mov_b32 m0, s8
	s_add_i32 s8, s8, 0x2000
	global_load_lds_dwordx4 v229, s[10:11]
	s_mov_b32 m0, s8
	s_add_u32 s10, s10, 0xd0000
	s_addc_u32 s11, s11, 0
	global_load_lds_dwordx4 v229, s[10:11]
	v_readlane_b32 s10, v252, 55
	v_readlane_b32 s11, v252, 56
	s_mul_i32 s42, s13, 0x9000
	s_lshl_b32 s101, s27, 1
	s_add_i32 s42, s42, s101
	s_add_i32 s8, s8, 0x2000
	s_add_u32 s10, s10, s42
	s_addc_u32 s11, s11, 0
	s_mov_b32 m0, s8
	s_add_i32 s8, s8, 0x2000
	global_load_lds_dwordx4 v254, s[10:11]
	s_mov_b32 m0, s8
	s_add_u32 s10, s10, 0x240000
	s_addc_u32 s11, s11, 0
	global_load_lds_dwordx4 v254, s[10:11]
	s_add_i32 s98, s98, 0x8000
	s_cmp_eq_u32 s98, 0x19000
	s_cselect_b32 s98, 0x1000, s98

.Lat_body:
	s_cmp_ge_i32 s70, s2
	s_cselect_b32 s27, 1, 0
	s_cmp_lt_u32 s70, 8
	s_cselect_b32 s42, 1, 0
	s_or_b32 s42, s42, s27
	s_add_i32 s101, s3, s70
	s_cmp_ge_u32 s101, s14
	s_cselect_b32 s101, 1, 0
	s_or_b32 s101, s101, s27
	s_and_b32 s42, s42, s101
	s_cmp_lg_u32 s42, 0
	s_cbranch_scc1 .Lat_merged
	s_cmp_ge_i32 s70, s2
	s_cselect_b64 s[8:9], -1, 0
	s_cmp_lt_i32 s70, s2
	s_cselect_b64 s[4:5], -1, 0
	s_cmp_lt_u32 s70, 8
	s_cselect_b64 s[10:11], -1, 0
	s_or_b64 s[10:11], s[8:9], s[10:11]
	v_cndmask_b32_e64 v162, 0, 1, s[4:5]
	s_andn2_b64 vcc, exec, s[10:11]
	v_cmp_ne_u32_e64 s[4:5], 1, v162
	s_cbranch_vccnz .LBB0_309
	s_waitcnt lgkmcnt(8)
	v_mfma_f32_16x16x32_bf16 v[162:165], v[142:145], v[50:53], 0
	s_and_b64 vcc, exec, s[4:5]
	v_mfma_f32_16x16x32_bf16 v[162:165], v[130:133], v[54:57], v[162:165]
	v_mfma_f32_16x16x32_bf16 v[162:165], v[134:137], v[58:61], v[162:165]
	v_mfma_f32_16x16x32_bf16 v[166:169], v[138:141], v[66:69], v[162:165]
	v_mfma_f32_16x16x32_bf16 v[162:165], v[158:161], v[50:53], 0
	v_mfma_f32_16x16x32_bf16 v[162:165], v[150:153], v[54:57], v[162:165]
	v_mfma_f32_16x16x32_bf16 v[162:165], v[154:157], v[58:61], v[162:165]
	v_mfma_f32_16x16x32_bf16 v[162:165], v[146:149], v[66:69], v[162:165]
	s_cbranch_vccnz .LBB0_307
	s_nop 7
	v_add_f32_e32 v208, v166, v213
	v_add_f32_e32 v206, v167, v214
	v_add_f32_e32 v209, v168, v215
	v_add_f32_e32 v207, v169, v216
	v_add_f32_e32 v211, v162, v217
	v_add_f32_e32 v210, v163, v218
	v_add_f32_e32 v212, v164, v219
	v_add_f32_e32 v189, v165, v220
	v_cndmask_b32_e64 v208, v253, v208, s[40:41]
	v_cndmask_b32_e64 v206, v253, v206, s[52:53]
	v_cndmask_b32_e64 v209, v253, v209, s[54:55]
	v_cndmask_b32_e64 v207, v253, v207, s[60:61]
	v_cndmask_b32_e64 v211, v253, v211, s[62:63]
	v_cndmask_b32_e64 v210, v253, v210, s[80:81]
	v_cndmask_b32_e64 v212, v253, v212, s[82:83]
	v_cndmask_b32_e64 v189, v253, v189, s[6:7]
	s_branch .LBB0_308

.LBB0_309:
	s_add_i32 s10, s3, s70
	s_cmp_ge_u32 s10, s14
	s_cselect_b64 s[10:11], -1, 0
	s_or_b64 s[8:9], s[8:9], s[10:11]
	s_andn2_b64 vcc, exec, s[8:9]
	s_cbranch_vccnz .LBB0_285
	s_waitcnt lgkmcnt(8)
	v_mfma_f32_16x16x32_bf16 v[142:145], v[142:145], v[78:81], 0
	s_and_b64 vcc, exec, s[4:5]
	v_mfma_f32_16x16x32_bf16 v[130:133], v[130:133], v[82:85], v[142:145]
	v_mfma_f32_16x16x32_bf16 v[130:133], v[134:137], v[86:89], v[130:133]
	v_mfma_f32_16x16x32_bf16 v[134:137], v[138:141], v[94:97], v[130:133]
	v_mfma_f32_16x16x32_bf16 v[130:133], v[158:161], v[78:81], 0
	v_mfma_f32_16x16x32_bf16 v[130:133], v[150:153], v[82:85], v[130:133]
	v_mfma_f32_16x16x32_bf16 v[130:133], v[154:157], v[86:89], v[130:133]
	v_mfma_f32_16x16x32_bf16 v[130:133], v[146:149], v[94:97], v[130:133]
	s_cbranch_vccnz .LBB0_327
	s_nop 7
	v_add_f32_e32 v140, v134, v221
	v_add_f32_e32 v138, v135, v222
	v_add_f32_e32 v141, v136, v223
	v_add_f32_e32 v139, v137, v224
	v_add_f32_e32 v143, v130, v225
	v_add_f32_e32 v142, v131, v226
	v_add_f32_e32 v145, v132, v227
	v_add_f32_e32 v144, v133, v228
	v_cndmask_b32_e64 v140, v253, v140, s[40:41]
	v_cndmask_b32_e64 v138, v253, v138, s[52:53]
	v_cndmask_b32_e64 v141, v253, v141, s[54:55]
	v_cndmask_b32_e64 v139, v253, v139, s[60:61]
	v_cndmask_b32_e64 v143, v253, v143, s[62:63]
	v_cndmask_b32_e64 v142, v253, v142, s[80:81]
	v_cndmask_b32_e64 v145, v253, v145, s[82:83]
	v_cndmask_b32_e64 v144, v253, v144, s[6:7]
	s_branch .LBB0_284

.LBB0_285:
	v_add_u32_e32 v188, 0x7c, v188
	s_cmp_eq_u32 s100, 0
	s_cbranch_scc1 .Lat_ctx_sub1
.Lat_tile_next:
	s_add_i32 s99, s99, 0x8000
	s_cmp_eq_u32 s99, 0x19000
	s_cselect_b32 s99, 0x1000, s99
	s_add_i32 s71, s71, 1
	s_add_i32 s27, s78, 4
	s_cmp_lt_u32 s71, s27
	s_cbranch_scc1 .Lat_tile_top
	s_branch .LBB0_279
.Lat_merged:
	s_waitcnt lgkmcnt(8)
	v_mfma_f32_16x16x32_bf16 v[162:165], v[142:145], v[50:53], 0
	v_mfma_f32_16x16x32_bf16 v[162:165], v[130:133], v[54:57], v[162:165]
	v_mfma_f32_16x16x32_bf16 v[162:165], v[134:137], v[58:61], v[162:165]
	v_mfma_f32_16x16x32_bf16 v[166:169], v[138:141], v[66:69], v[162:165]
	v_mfma_f32_16x16x32_bf16 v[162:165], v[158:161], v[50:53], 0
	v_mfma_f32_16x16x32_bf16 v[162:165], v[150:153], v[54:57], v[162:165]
	v_mfma_f32_16x16x32_bf16 v[162:165], v[154:157], v[58:61], v[162:165]
	v_mfma_f32_16x16x32_bf16 v[162:165], v[146:149], v[66:69], v[162:165]
	v_mfma_f32_16x16x32_bf16 v[142:145], v[142:145], v[78:81], 0
	v_mfma_f32_16x16x32_bf16 v[130:133], v[130:133], v[82:85], v[142:145]
	v_mfma_f32_16x16x32_bf16 v[130:133], v[134:137], v[86:89], v[130:133]
	v_mfma_f32_16x16x32_bf16 v[134:137], v[138:141], v[94:97], v[130:133]
	v_mfma_f32_16x16x32_bf16 v[130:133], v[158:161], v[78:81], 0
	v_mfma_f32_16x16x32_bf16 v[130:133], v[150:153], v[82:85], v[130:133]
	v_mfma_f32_16x16x32_bf16 v[130:133], v[154:157], v[86:89], v[130:133]
	v_mfma_f32_16x16x32_bf16 v[130:133], v[146:149], v[94:97], v[130:133]
	s_cmp_ge_i32 s70, s2
	s_cbranch_scc1 .Lat_merged_ctx
	s_nop 7
	v_add_f32_e32 v208, v166, v213
	v_add_f32_e32 v140, v134, v221
	v_add_f32_e32 v206, v167, v214
	v_add_f32_e32 v138, v135, v222
	v_add_f32_e32 v209, v168, v215
	v_add_f32_e32 v141, v136, v223
	v_add_f32_e32 v207, v169, v216
	v_add_f32_e32 v139, v137, v224
	v_add_f32_e32 v211, v162, v217
	v_add_f32_e32 v143, v130, v225
	v_add_f32_e32 v210, v163, v218
	v_add_f32_e32 v142, v131, v226
	v_add_f32_e32 v212, v164, v219
	v_add_f32_e32 v145, v132, v227
	v_add_f32_e32 v189, v165, v220
	v_add_f32_e32 v144, v133, v228
	v_cndmask_b32_e64 v208, v253, v208, s[40:41]
	v_cndmask_b32_e64 v140, v253, v140, s[40:41]
	v_cndmask_b32_e64 v206, v253, v206, s[52:53]
	v_cndmask_b32_e64 v138, v253, v138, s[52:53]
	v_cndmask_b32_e64 v209, v253, v209, s[54:55]
	v_cndmask_b32_e64 v141, v253, v141, s[54:55]
	v_cndmask_b32_e64 v207, v253, v207, s[60:61]
	v_cndmask_b32_e64 v139, v253, v139, s[60:61]
	v_cndmask_b32_e64 v211, v253, v211, s[62:63]
	v_cndmask_b32_e64 v143, v253, v143, s[62:63]
	v_cndmask_b32_e64 v210, v253, v210, s[80:81]
	v_cndmask_b32_e64 v142, v253, v142, s[80:81]
	v_cndmask_b32_e64 v212, v253, v212, s[82:83]
	v_cndmask_b32_e64 v145, v253, v145, s[82:83]
	v_cndmask_b32_e64 v189, v253, v189, s[6:7]
	v_cndmask_b32_e64 v144, v253, v144, s[6:7]
	v_max3_f32 v162, v206, v208, v207
	v_max3_f32 v130, v138, v140, v139
	v_max3_f32 v163, v209, v189, v212
	v_max3_f32 v131, v141, v144, v145
	v_max_f32_e32 v164, v211, v210
	v_max_f32_e32 v132, v143, v142
	v_max3_f32 v162, v162, v163, v164
	v_max3_f32 v130, v130, v131, v132
	ds_bpermute_b32 v163, v171, v162
	ds_bpermute_b32 v131, v171, v130
	s_waitcnt lgkmcnt(0)
	s_waitcnt lgkmcnt(0)
	v_max_f32_e32 v162, v162, v163
	v_max_f32_e32 v130, v130, v131
	ds_bpermute_b32 v163, v199, v162
	ds_bpermute_b32 v131, v199, v130
	s_waitcnt lgkmcnt(0)
	s_waitcnt lgkmcnt(0)
	v_max3_f32 v167, v203, v162, v163
	v_max3_f32 v135, v185, v130, v131
	v_sub_f32_e32 v166, v209, v167
	v_sub_f32_e32 v134, v141, v135
	v_mul_f32_e32 v166, 0x3fb8aa3b, v166
	v_mul_f32_e32 v134, 0x3fb8aa3b, v134
	v_exp_f32_e32 v168, v166
	v_exp_f32_e32 v136, v134
	v_sub_f32_e32 v166, v207, v167
	v_sub_f32_e32 v134, v139, v135
	v_mul_f32_e32 v166, 0x3fb8aa3b, v166
	v_mul_f32_e32 v134, 0x3fb8aa3b, v134
	v_sub_f32_e32 v163, v208, v167
	v_sub_f32_e32 v131, v140, v135
	v_exp_f32_e32 v169, v166
	v_exp_f32_e32 v137, v134
	v_sub_f32_e32 v166, v211, v167
	v_sub_f32_e32 v134, v143, v135
	v_mul_f32_e32 v163, 0x3fb8aa3b, v163
	v_mul_f32_e32 v131, 0x3fb8aa3b, v131
	v_sub_f32_e32 v165, v206, v167
	v_sub_f32_e32 v133, v138, v135
	v_mul_f32_e32 v166, 0x3fb8aa3b, v166
	v_mul_f32_e32 v134, 0x3fb8aa3b, v134
	v_sub_f32_e32 v162, v203, v167
	v_exp_f32_e32 v131, v131
	v_exp_f32_e32 v163, v163
	v_mul_f32_e32 v133, 0x3fb8aa3b, v133
	v_mul_f32_e32 v165, 0x3fb8aa3b, v165
	v_exp_f32_e32 v138, v134
	v_exp_f32_e32 v203, v166
	v_sub_f32_e32 v134, v142, v135
	v_sub_f32_e32 v166, v210, v167
	v_exp_f32_e32 v133, v133
	v_exp_f32_e32 v165, v165
	v_mul_f32_e32 v134, 0x3fb8aa3b, v134
	v_mul_f32_e32 v166, 0x3fb8aa3b, v166
	v_exp_f32_e32 v139, v134
	v_exp_f32_e32 v206, v166
	v_sub_f32_e32 v134, v145, v135
	v_sub_f32_e32 v166, v212, v167
	v_mul_f32_e32 v134, 0x3fb8aa3b, v134
	v_mul_f32_e32 v166, 0x3fb8aa3b, v166
	v_sub_f32_e32 v130, v185, v135
	v_add_f32_e32 v164, 0, v163
	v_add_f32_e32 v132, 0, v131
	v_exp_f32_e32 v207, v166
	v_exp_f32_e32 v140, v134
	v_sub_f32_e32 v166, v189, v167
	v_sub_f32_e32 v134, v144, v135
	v_mul_f32_e32 v162, 0x3fb8aa3b, v162
	v_mul_f32_e32 v130, 0x3fb8aa3b, v130
	v_add_f32_e32 v164, v165, v164
	v_add_f32_e32 v132, v133, v132
	v_mul_f32_e32 v166, 0x3fb8aa3b, v166
	v_mul_f32_e32 v134, 0x3fb8aa3b, v134
	v_add_f32_e32 v164, v168, v164
	v_add_f32_e32 v132, v136, v132
	v_exp_f32_e32 v189, v166
	v_exp_f32_e32 v141, v134
	v_exp_f32_e32 v166, v162
	v_exp_f32_e32 v134, v130
	v_add_f32_e32 v164, v169, v164
	v_add_f32_e32 v132, v137, v132
	v_add_f32_e32 v164, v203, v164
	v_add_f32_e32 v132, v138, v132
	v_add_f32_e32 v164, v206, v164
	v_add_f32_e32 v132, v139, v132
	v_add_f32_e32 v164, v207, v164
	v_add_f32_e32 v132, v140, v132
	v_pk_mul_f32 v[92:93], v[92:93], v[166:167] op_sel_hi:[1,0]
	v_pk_mul_f32 v[32:33], v[32:33], v[134:135] op_sel_hi:[1,0]
	v_pk_mul_f32 v[90:91], v[90:91], v[166:167] op_sel_hi:[1,0]
	v_pk_mul_f32 v[30:31], v[30:31], v[134:135] op_sel_hi:[1,0]
	v_pk_mul_f32 v[76:77], v[76:77], v[166:167] op_sel_hi:[1,0]
	v_pk_mul_f32 v[28:29], v[28:29], v[134:135] op_sel_hi:[1,0]
	v_pk_mul_f32 v[74:75], v[74:75], v[166:167] op_sel_hi:[1,0]
	v_pk_mul_f32 v[26:27], v[26:27], v[134:135] op_sel_hi:[1,0]
	v_pk_mul_f32 v[72:73], v[72:73], v[166:167] op_sel_hi:[1,0]
	v_pk_mul_f32 v[24:25], v[24:25], v[134:135] op_sel_hi:[1,0]
	v_pk_mul_f32 v[70:71], v[70:71], v[166:167] op_sel_hi:[1,0]
	v_pk_mul_f32 v[22:23], v[22:23], v[134:135] op_sel_hi:[1,0]
	v_pk_mul_f32 v[64:65], v[64:65], v[166:167] op_sel_hi:[1,0]
	v_pk_mul_f32 v[20:21], v[20:21], v[134:135] op_sel_hi:[1,0]
	v_pk_mul_f32 v[62:63], v[62:63], v[166:167] op_sel_hi:[1,0]
	v_pk_mul_f32 v[18:19], v[18:19], v[134:135] op_sel_hi:[1,0]
	v_pk_mul_f32 v[48:49], v[48:49], v[166:167] op_sel_hi:[1,0]
	v_pk_mul_f32 v[16:17], v[16:17], v[134:135] op_sel_hi:[1,0]
	v_pk_mul_f32 v[46:47], v[46:47], v[166:167] op_sel_hi:[1,0]
	v_pk_mul_f32 v[14:15], v[14:15], v[134:135] op_sel_hi:[1,0]
	v_pk_mul_f32 v[44:45], v[44:45], v[166:167] op_sel_hi:[1,0]
	v_pk_mul_f32 v[12:13], v[12:13], v[134:135] op_sel_hi:[1,0]
	v_pk_mul_f32 v[42:43], v[42:43], v[166:167] op_sel_hi:[1,0]
	v_pk_mul_f32 v[10:11], v[10:11], v[134:135] op_sel_hi:[1,0]
	v_pk_mul_f32 v[40:41], v[40:41], v[166:167] op_sel_hi:[1,0]
	v_pk_mul_f32 v[8:9], v[8:9], v[134:135] op_sel_hi:[1,0]
	v_pk_mul_f32 v[38:39], v[38:39], v[166:167] op_sel_hi:[1,0]
	v_pk_mul_f32 v[6:7], v[6:7], v[134:135] op_sel_hi:[1,0]
	v_pk_mul_f32 v[36:37], v[36:37], v[166:167] op_sel_hi:[1,0]
	v_pk_mul_f32 v[4:5], v[4:5], v[134:135] op_sel_hi:[1,0]
	v_pk_mul_f32 v[34:35], v[34:35], v[166:167] op_sel_hi:[1,0]
	v_pk_mul_f32 v[2:3], v[2:3], v[134:135] op_sel_hi:[1,0]
	v_add_f32_e32 v208, v189, v164
	v_add_f32_e32 v142, v141, v132
	v_cvt_pk_bf16_f32 v162, v163, v165
	v_cvt_pk_bf16_f32 v130, v131, v133
	v_cvt_pk_bf16_f32 v163, v168, v169
	v_cvt_pk_bf16_f32 v131, v136, v137
	v_cvt_pk_bf16_f32 v164, v203, v206
	v_cvt_pk_bf16_f32 v132, v138, v139
	v_cvt_pk_bf16_f32 v165, v207, v189
	v_cvt_pk_bf16_f32 v133, v140, v141
	v_fmac_f32_e32 v208, v201, v166
	v_fmac_f32_e32 v142, v175, v134
	v_mfma_f32_16x16x32_bf16 v[90:93], v[126:129], v[162:165], v[90:93]
	v_mfma_f32_16x16x32_bf16 v[30:33], v[126:129], v[130:133], v[30:33]
	v_mov_b32_e32 v201, v208
	v_mov_b32_e32 v175, v142
	v_mov_b32_e32 v203, v167
	v_mov_b32_e32 v185, v135
	v_mfma_f32_16x16x32_bf16 v[74:77], v[122:125], v[162:165], v[74:77]
	v_mfma_f32_16x16x32_bf16 v[26:29], v[122:125], v[130:133], v[26:29]
	v_mfma_f32_16x16x32_bf16 v[70:73], v[118:121], v[162:165], v[70:73]
	v_mfma_f32_16x16x32_bf16 v[22:25], v[118:121], v[130:133], v[22:25]
	v_mfma_f32_16x16x32_bf16 v[62:65], v[114:117], v[162:165], v[62:65]
	v_mfma_f32_16x16x32_bf16 v[18:21], v[114:117], v[130:133], v[18:21]
	v_mfma_f32_16x16x32_bf16 v[46:49], v[110:113], v[162:165], v[46:49]
	v_mfma_f32_16x16x32_bf16 v[14:17], v[110:113], v[130:133], v[14:17]
	v_mfma_f32_16x16x32_bf16 v[42:45], v[106:109], v[162:165], v[42:45]
	v_mfma_f32_16x16x32_bf16 v[10:13], v[106:109], v[130:133], v[10:13]
	v_mfma_f32_16x16x32_bf16 v[38:41], v[102:105], v[162:165], v[38:41]
	v_mfma_f32_16x16x32_bf16 v[6:9], v[102:105], v[130:133], v[6:9]
	v_mfma_f32_16x16x32_bf16 v[34:37], v[98:101], v[162:165], v[34:37]
	v_mfma_f32_16x16x32_bf16 v[2:5], v[98:101], v[130:133], v[2:5]
	s_branch .LBB0_285
.Lat_merged_ctx:
	s_nop 7
	v_mov_b32_e32 v189, v165
	v_mov_b32_e32 v144, v133
	v_mov_b32_e32 v212, v164
	v_mov_b32_e32 v145, v132
	v_mov_b32_e32 v210, v163
	v_mov_b32_e32 v142, v131
	v_mov_b32_e32 v211, v162
	v_mov_b32_e32 v143, v130
	v_mov_b32_e32 v207, v169
	v_mov_b32_e32 v139, v137
	v_mov_b32_e32 v209, v168
	v_mov_b32_e32 v141, v136
	v_mov_b32_e32 v206, v167
	v_mov_b32_e32 v138, v135
	v_mov_b32_e32 v208, v166
	v_mov_b32_e32 v140, v134
	v_max3_f32 v162, v206, v208, v207
	v_max3_f32 v130, v138, v140, v139
	v_max3_f32 v163, v209, v189, v212
	v_max3_f32 v131, v141, v144, v145
	v_max_f32_e32 v164, v211, v210
	v_max_f32_e32 v132, v143, v142
	v_max3_f32 v162, v162, v163, v164
	v_max3_f32 v130, v130, v131, v132
	ds_bpermute_b32 v163, v171, v162
	ds_bpermute_b32 v131, v171, v130
	s_waitcnt lgkmcnt(0)
	s_waitcnt lgkmcnt(0)
	v_max_f32_e32 v162, v162, v163
	v_max_f32_e32 v130, v130, v131
	ds_bpermute_b32 v163, v199, v162
	ds_bpermute_b32 v131, v199, v130
	s_waitcnt lgkmcnt(0)
	s_waitcnt lgkmcnt(0)
	v_max3_f32 v167, v203, v162, v163
	v_max3_f32 v135, v185, v130, v131
	v_sub_f32_e32 v166, v209, v167
	v_sub_f32_e32 v134, v141, v135
	v_mul_f32_e32 v166, 0x3fb8aa3b, v166
	v_mul_f32_e32 v134, 0x3fb8aa3b, v134
	v_exp_f32_e32 v168, v166
	v_exp_f32_e32 v136, v134
	v_sub_f32_e32 v166, v207, v167
	v_sub_f32_e32 v134, v139, v135
	v_mul_f32_e32 v166, 0x3fb8aa3b, v166
	v_mul_f32_e32 v134, 0x3fb8aa3b, v134
	v_sub_f32_e32 v163, v208, v167
	v_sub_f32_e32 v131, v140, v135
	v_exp_f32_e32 v169, v166
	v_exp_f32_e32 v137, v134
	v_sub_f32_e32 v166, v211, v167
	v_sub_f32_e32 v134, v143, v135
	v_mul_f32_e32 v163, 0x3fb8aa3b, v163
	v_mul_f32_e32 v131, 0x3fb8aa3b, v131
	v_sub_f32_e32 v165, v206, v167
	v_sub_f32_e32 v133, v138, v135
	v_mul_f32_e32 v166, 0x3fb8aa3b, v166
	v_mul_f32_e32 v134, 0x3fb8aa3b, v134
	v_sub_f32_e32 v162, v203, v167
	v_exp_f32_e32 v131, v131
	v_exp_f32_e32 v163, v163
	v_mul_f32_e32 v133, 0x3fb8aa3b, v133
	v_mul_f32_e32 v165, 0x3fb8aa3b, v165
	v_exp_f32_e32 v138, v134
	v_exp_f32_e32 v203, v166
	v_sub_f32_e32 v134, v142, v135
	v_sub_f32_e32 v166, v210, v167
	v_exp_f32_e32 v133, v133
	v_exp_f32_e32 v165, v165
	v_mul_f32_e32 v134, 0x3fb8aa3b, v134
	v_mul_f32_e32 v166, 0x3fb8aa3b, v166
	v_exp_f32_e32 v139, v134
	v_exp_f32_e32 v206, v166
	v_sub_f32_e32 v134, v145, v135
	v_sub_f32_e32 v166, v212, v167
	v_mul_f32_e32 v134, 0x3fb8aa3b, v134
	v_mul_f32_e32 v166, 0x3fb8aa3b, v166
	v_sub_f32_e32 v130, v185, v135
	v_add_f32_e32 v164, 0, v163
	v_add_f32_e32 v132, 0, v131
	v_exp_f32_e32 v207, v166
	v_exp_f32_e32 v140, v134
	v_sub_f32_e32 v166, v189, v167
	v_sub_f32_e32 v134, v144, v135
	v_mul_f32_e32 v162, 0x3fb8aa3b, v162
	v_mul_f32_e32 v130, 0x3fb8aa3b, v130
	v_add_f32_e32 v164, v165, v164
	v_add_f32_e32 v132, v133, v132
	v_mul_f32_e32 v166, 0x3fb8aa3b, v166
	v_mul_f32_e32 v134, 0x3fb8aa3b, v134
	v_add_f32_e32 v164, v168, v164
	v_add_f32_e32 v132, v136, v132
	v_exp_f32_e32 v189, v166
	v_exp_f32_e32 v141, v134
	v_exp_f32_e32 v166, v162
	v_exp_f32_e32 v134, v130
	v_add_f32_e32 v164, v169, v164
	v_add_f32_e32 v132, v137, v132
	v_add_f32_e32 v164, v203, v164
	v_add_f32_e32 v132, v138, v132
	v_add_f32_e32 v164, v206, v164
	v_add_f32_e32 v132, v139, v132
	v_add_f32_e32 v164, v207, v164
	v_add_f32_e32 v132, v140, v132
	v_pk_mul_f32 v[92:93], v[92:93], v[166:167] op_sel_hi:[1,0]
	v_pk_mul_f32 v[32:33], v[32:33], v[134:135] op_sel_hi:[1,0]
	v_pk_mul_f32 v[90:91], v[90:91], v[166:167] op_sel_hi:[1,0]
	v_pk_mul_f32 v[30:31], v[30:31], v[134:135] op_sel_hi:[1,0]
	v_pk_mul_f32 v[76:77], v[76:77], v[166:167] op_sel_hi:[1,0]
	v_pk_mul_f32 v[28:29], v[28:29], v[134:135] op_sel_hi:[1,0]
	v_pk_mul_f32 v[74:75], v[74:75], v[166:167] op_sel_hi:[1,0]
	v_pk_mul_f32 v[26:27], v[26:27], v[134:135] op_sel_hi:[1,0]
	v_pk_mul_f32 v[72:73], v[72:73], v[166:167] op_sel_hi:[1,0]
	v_pk_mul_f32 v[24:25], v[24:25], v[134:135] op_sel_hi:[1,0]
	v_pk_mul_f32 v[70:71], v[70:71], v[166:167] op_sel_hi:[1,0]
	v_pk_mul_f32 v[22:23], v[22:23], v[134:135] op_sel_hi:[1,0]
	v_pk_mul_f32 v[64:65], v[64:65], v[166:167] op_sel_hi:[1,0]
	v_pk_mul_f32 v[20:21], v[20:21], v[134:135] op_sel_hi:[1,0]
	v_pk_mul_f32 v[62:63], v[62:63], v[166:167] op_sel_hi:[1,0]
	v_pk_mul_f32 v[18:19], v[18:19], v[134:135] op_sel_hi:[1,0]
	v_pk_mul_f32 v[48:49], v[48:49], v[166:167] op_sel_hi:[1,0]
	v_pk_mul_f32 v[16:17], v[16:17], v[134:135] op_sel_hi:[1,0]
	v_pk_mul_f32 v[46:47], v[46:47], v[166:167] op_sel_hi:[1,0]
	v_pk_mul_f32 v[14:15], v[14:15], v[134:135] op_sel_hi:[1,0]
	v_pk_mul_f32 v[44:45], v[44:45], v[166:167] op_sel_hi:[1,0]
	v_pk_mul_f32 v[12:13], v[12:13], v[134:135] op_sel_hi:[1,0]
	v_pk_mul_f32 v[42:43], v[42:43], v[166:167] op_sel_hi:[1,0]
	v_pk_mul_f32 v[10:11], v[10:11], v[134:135] op_sel_hi:[1,0]
	v_pk_mul_f32 v[40:41], v[40:41], v[166:167] op_sel_hi:[1,0]
	v_pk_mul_f32 v[8:9], v[8:9], v[134:135] op_sel_hi:[1,0]
	v_pk_mul_f32 v[38:39], v[38:39], v[166:167] op_sel_hi:[1,0]
	v_pk_mul_f32 v[6:7], v[6:7], v[134:135] op_sel_hi:[1,0]
	v_pk_mul_f32 v[36:37], v[36:37], v[166:167] op_sel_hi:[1,0]
	v_pk_mul_f32 v[4:5], v[4:5], v[134:135] op_sel_hi:[1,0]
	v_pk_mul_f32 v[34:35], v[34:35], v[166:167] op_sel_hi:[1,0]
	v_pk_mul_f32 v[2:3], v[2:3], v[134:135] op_sel_hi:[1,0]
	v_add_f32_e32 v208, v189, v164
	v_add_f32_e32 v142, v141, v132
	v_cvt_pk_bf16_f32 v162, v163, v165
	v_cvt_pk_bf16_f32 v130, v131, v133
	v_cvt_pk_bf16_f32 v163, v168, v169
	v_cvt_pk_bf16_f32 v131, v136, v137
	v_cvt_pk_bf16_f32 v164, v203, v206
	v_cvt_pk_bf16_f32 v132, v138, v139
	v_cvt_pk_bf16_f32 v165, v207, v189
	v_cvt_pk_bf16_f32 v133, v140, v141
	v_fmac_f32_e32 v208, v201, v166
	v_fmac_f32_e32 v142, v175, v134
	v_mfma_f32_16x16x32_bf16 v[90:93], v[126:129], v[162:165], v[90:93]
	v_mfma_f32_16x16x32_bf16 v[30:33], v[126:129], v[130:133], v[30:33]
	v_mov_b32_e32 v201, v208
	v_mov_b32_e32 v175, v142
	v_mov_b32_e32 v203, v167
	v_mov_b32_e32 v185, v135
	v_mfma_f32_16x16x32_bf16 v[74:77], v[122:125], v[162:165], v[74:77]
	v_mfma_f32_16x16x32_bf16 v[26:29], v[122:125], v[130:133], v[26:29]
	v_mfma_f32_16x16x32_bf16 v[70:73], v[118:121], v[162:165], v[70:73]
	v_mfma_f32_16x16x32_bf16 v[22:25], v[118:121], v[130:133], v[22:25]
	v_mfma_f32_16x16x32_bf16 v[62:65], v[114:117], v[162:165], v[62:65]
	v_mfma_f32_16x16x32_bf16 v[18:21], v[114:117], v[130:133], v[18:21]
	v_mfma_f32_16x16x32_bf16 v[46:49], v[110:113], v[162:165], v[46:49]
	v_mfma_f32_16x16x32_bf16 v[14:17], v[110:113], v[130:133], v[14:17]
	v_mfma_f32_16x16x32_bf16 v[42:45], v[106:109], v[162:165], v[42:45]
	v_mfma_f32_16x16x32_bf16 v[10:13], v[106:109], v[130:133], v[10:13]
	v_mfma_f32_16x16x32_bf16 v[38:41], v[102:105], v[162:165], v[38:41]
	v_mfma_f32_16x16x32_bf16 v[6:9], v[102:105], v[130:133], v[6:9]
	v_mfma_f32_16x16x32_bf16 v[34:37], v[98:101], v[162:165], v[34:37]
	v_mfma_f32_16x16x32_bf16 v[2:5], v[98:101], v[130:133], v[2:5]
	s_branch .LBB0_285
